# group-local barriers at P1->P2, P9->P10, P11->P12 (same-XCC producer/consumer groups, runtime placement check with full-barrier fallback)
# speedup vs baseline: 1.0028x; 1.0028x over previous
.LBB0_35:
	s_or_b64 exec, exec, s[10:11]
	s_add_u32 s75, s66, 0x1000
	s_addc_u32 s76, s67, 0
	s_waitcnt vmcnt(0)
	s_getreg_b32 s98, hwreg(HW_REG_XCC_ID, 0, 4)
	s_and_saveexec_b64 s[0:1], s[46:47]
	s_cbranch_execz .Lgb_mask_done
	s_lshl_b32 s98, 1, s98
	s_and_b32 s99, s2, 7
	s_lshl_b32 s99, s99, 6
	s_add_i32 s99, s99, 0x4800
	v_mov_b32_e32 v250, s99
	v_mov_b32_e32 v251, s98
	global_atomic_or v250, v251, s[66:67]

.LBB0_401:
	s_or_b64 exec, exec, s[0:1]
	v_mov_b32_e32 v250, 0x4800
	global_load_dword v242, v250, s[66:67] offset:0 sc1
	global_load_dword v243, v250, s[66:67] offset:64 sc1
	global_load_dword v244, v250, s[66:67] offset:128 sc1
	global_load_dword v245, v250, s[66:67] offset:192 sc1
	global_load_dword v246, v250, s[66:67] offset:256 sc1
	global_load_dword v247, v250, s[66:67] offset:320 sc1
	global_load_dword v248, v250, s[66:67] offset:384 sc1
	global_load_dword v249, v250, s[66:67] offset:448 sc1
	s_mov_b32 s100, 1
	s_waitcnt vmcnt(0)
	v_readfirstlane_b32 s98, v242
	s_bcnt1_i32_b32 s98, s98
	s_cmp_eq_u32 s98, 1
	s_cselect_b32 s100, s100, 0
	v_readfirstlane_b32 s98, v243
	s_bcnt1_i32_b32 s98, s98
	s_cmp_eq_u32 s98, 1
	s_cselect_b32 s100, s100, 0
	v_readfirstlane_b32 s98, v244
	s_bcnt1_i32_b32 s98, s98
	s_cmp_eq_u32 s98, 1
	s_cselect_b32 s100, s100, 0
	v_readfirstlane_b32 s98, v245
	s_bcnt1_i32_b32 s98, s98
	s_cmp_eq_u32 s98, 1
	s_cselect_b32 s100, s100, 0
	v_readfirstlane_b32 s98, v246
	s_bcnt1_i32_b32 s98, s98
	s_cmp_eq_u32 s98, 1
	s_cselect_b32 s100, s100, 0
	v_readfirstlane_b32 s98, v247
	s_bcnt1_i32_b32 s98, s98
	s_cmp_eq_u32 s98, 1
	s_cselect_b32 s100, s100, 0
	v_readfirstlane_b32 s98, v248
	s_bcnt1_i32_b32 s98, s98
	s_cmp_eq_u32 s98, 1
	s_cselect_b32 s100, s100, 0
	v_readfirstlane_b32 s98, v249
	s_bcnt1_i32_b32 s98, s98
	s_cmp_eq_u32 s98, 1
	s_cselect_b32 s100, s100, 0
	s_and_b32 s98, s64, 7
	s_cmp_eq_u32 s98, 0
	s_cselect_b32 s100, s100, 0
	s_mov_b64 s[4:5], s[66:67]
	s_mov_b64 s[0:1], s[68:69]
	s_waitcnt lgkmcnt(0)
	v_mov_b32_e32 v0, v194
	s_mov_b32 s36, s64
	v_mov_b32_e32 v9, v194
	s_cmpk_lt_i32 s2, 0x580
	s_barrier
	s_cselect_b64 s[56:57], -1, 0
	s_cmpk_gt_i32 s2, 0x57f
	v_readfirstlane_b32 s17, v9
	s_cbranch_scc1 .LBB0_417
	v_lshlrev_b32_e32 v0, 4, v9
	v_add_u32_e32 v1, 0x2000, v0
	v_ashrrev_i32_e32 v2, 31, v1
	v_lshrrev_b32_e32 v2, 22, v2
	v_add_u32_e32 v2, v1, v2
	v_ashrrev_i32_e32 v8, 10, v2
	v_mul_i32_i24_e32 v2, 0x400, v8
	v_sub_u32_e32 v1, v1, v2
	v_lshrrev_b32_e32 v2, 4, v1
	v_bitop3_b32 v1, v2, v1, 32 bitop3:0x6c
	v_ashrrev_i32_e32 v2, 31, v1
	v_lshrrev_b32_e32 v2, 26, v2
	v_add_u32_e32 v2, v1, v2
	v_lshlrev_b32_e32 v3, 3, v8
	v_ashrrev_i32_e32 v10, 6, v2
	v_and_b32_e32 v3, -16, v3
	v_add_u32_e32 v3, v10, v3
	v_and_b32_e32 v4, 3, v10
	s_mov_b32 s0, 0x1fffe0
	v_lshrrev_b32_e32 v5, 2, v3
	v_lshlrev_b32_e32 v6, 1, v3
	v_and_b32_e32 v2, 0xc0, v2
	v_and_or_b32 v4, v3, s0, v4
	v_and_b32_e32 v5, 4, v5
	v_and_b32_e32 v6, 24, v6
	v_sub_u32_e32 v1, v1, v2
	v_mov_b32_e32 v2, 1
	v_or3_b32 v4, v4, v5, v6
	v_lshlrev_b32_e32 v5, 5, v8
	v_ashrrev_i16_sdwa v1, v2, sext(v1) dst_sel:DWORD dst_unused:UNUSED_PAD src0_sel:DWORD src1_sel:BYTE_0
	v_and_b32_e32 v5, 32, v5
	v_bfe_i32 v11, v1, 0, 16
	v_add_lshl_u32 v1, v5, v11, 1
	v_lshl_add_u32 v128, v4, 11, v1
	v_lshl_add_u32 v130, v3, 11, v1
	v_bfe_i32 v1, v9, 27, 1
	v_lshrrev_b32_e32 v1, 22, v1
	v_add_u32_e32 v1, v0, v1
	v_and_b32_e32 v1, 0xfffffc00, v1
	v_sub_u32_e32 v0, v0, v1
	v_lshrrev_b32_e32 v1, 4, v0
	v_ashrrev_i32_e32 v3, 31, v9
	v_bitop3_b32 v0, v1, v0, 32 bitop3:0x6c
	v_lshrrev_b32_e32 v3, 26, v3
	v_ashrrev_i32_e32 v1, 31, v0
	v_add_u32_e32 v3, v9, v3
	v_lshrrev_b32_e32 v1, 26, v1
	v_ashrrev_i32_e32 v13, 6, v3
	s_add_u32 s37, s4, 0x3800000
	v_add_u32_e32 v1, v0, v1
	v_lshlrev_b32_e32 v3, 3, v13
	s_addc_u32 s38, s5, 0
	v_ashrrev_i32_e32 v12, 6, v1
	v_and_b32_e32 v3, -16, v3
	s_add_u32 s39, s4, 0x100000
	v_add_u32_e32 v3, v12, v3
	v_and_b32_e32 v4, 3, v12
	s_addc_u32 s40, s5, 0
	v_and_or_b32 v4, v3, s0, v4
	s_lshr_b32 s0, s3, 29
	s_add_i32 s0, s2, s0
	s_ashr_i32 s12, s17, 6
	s_ashr_i32 s1, s0, 3
	s_and_b32 s0, s0, -8
	s_ashr_i32 s18, s17, 8
	s_lshl_b32 s41, s12, 10
	s_sub_i32 s0, s2, s0
	s_cmp_lt_i32 s0, 0
	s_movk_i32 s42, 0xb1
	s_cselect_b32 s6, s42, 0xb0
	s_mul_i32 s0, s0, s6
	s_add_i32 s0, s0, s1
	s_mul_hi_i32 s1, s0, 0x2e8ba2e9
	s_lshr_b32 s6, s1, 31
	s_ashr_i32 s1, s1, 5
	s_add_i32 s1, s1, s6
	s_lshl_b32 s6, s1, 3
	s_mulk_i32 s1, 0xb0
	s_sub_i32 s0, s0, s1
	s_sext_i32_i16 s1, s0
	s_bfe_u32 s1, s1, 0x3001c
	s_add_i32 s1, s0, s1
	s_sext_i32_i16 s7, s1
	s_and_b32 s1, s1, 0xfff8
	s_sub_i32 s0, s0, s1
	s_sext_i32_i16 s0, s0
	v_lshrrev_b32_e32 v5, 2, v3
	v_lshlrev_b32_e32 v6, 1, v3
	v_and_b32_e32 v1, 0xc0, v1
	s_lshr_b32 s16, s7, 3
	s_add_i32 s26, s6, s0
	v_and_b32_e32 v5, 4, v5
	v_and_b32_e32 v6, 24, v6
	v_sub_u32_e32 v0, v0, v1
	s_ashr_i32 s27, s26, 31
	s_bfe_i64 s[6:7], s[16:17], 0x100000
	v_or3_b32 v4, v4, v5, v6
	v_lshlrev_b32_e32 v5, 5, v13
	v_ashrrev_i16_sdwa v0, v2, sext(v0) dst_sel:DWORD dst_unused:UNUSED_PAD src0_sel:DWORD src1_sel:BYTE_0
	s_lshl_b64 s[0:1], s[26:27], 19
	s_lshl_b64 s[6:7], s[6:7], 19
	v_and_b32_e32 v5, 32, v5
	v_bfe_i32 v14, v0, 0, 16
	s_add_u32 s30, s39, s6
	v_add_lshl_u32 v0, v5, v14, 1
	s_addc_u32 s31, s40, s7
	s_add_i32 s27, s41, 0
	v_lshl_add_u32 v132, v4, 11, v0
	s_add_i32 m0, s27, 0x10000
	v_lshl_add_u32 v134, v3, 11, v0
	global_load_lds_dwordx4 v132, s[30:31]
	s_add_i32 m0, s27, 0x12000
	s_add_u32 s6, s30, 0x40000
	global_load_lds_dwordx4 v128, s[30:31]
	s_addc_u32 s7, s31, 0
	s_add_i32 m0, s27, 0x14000
	v_mov_b32_e32 v133, 0
	global_load_lds_dwordx4 v132, s[6:7]
	s_add_i32 m0, s27, 0x16000
	s_add_u32 s28, s37, s0
	s_addc_u32 s29, s38, s1
	s_add_i32 s43, s27, 0x2000
	global_load_lds_dwordx4 v128, s[6:7]
	s_mov_b32 m0, s27
	s_add_u32 s0, s28, 0x40000
	global_load_lds_dwordx4 v134, s[28:29]
	s_mov_b32 m0, s43
	s_addc_u32 s1, s29, 0
	s_add_i32 s44, s27, 0x4000
	global_load_lds_dwordx4 v130, s[28:29]
	s_mov_b32 m0, s44
	s_add_i32 s45, s27, 0x6000
	global_load_lds_dwordx4 v134, s[0:1]
	s_mov_b32 m0, s45
	v_mov_b32_e32 v129, v133
	global_load_lds_dwordx4 v130, s[0:1]
	v_mov_b32_e32 v135, v133
	v_mov_b32_e32 v131, v133
	s_cmp_eq_u32 s18, 1
	s_mov_b32 s50, 0
	v_lshl_add_u64 v[6:7], s[30:31], 0, v[132:133]
	v_lshl_add_u64 v[4:5], s[30:31], 0, v[128:129]
	v_lshl_add_u64 v[0:1], s[28:29], 0, v[134:135]
	s_cselect_b64 s[0:1], -1, 0
	s_cmp_lg_u32 s18, 1
	v_lshl_add_u64 v[2:3], s[28:29], 0, v[130:131]
	s_cbranch_scc1 .LBB0_404
	s_barrier

.LBB0_457:
	s_cmp_eq_u32 s100, 1
	s_cbranch_scc0 .Lgb_full_0
	s_waitcnt vmcnt(0)
	s_barrier
	s_and_saveexec_b64 s[0:1], s[46:47]
	s_cbranch_execz .Lgb_done_0
	s_and_b32 s98, s2, 7
	s_lshl_b32 s98, s98, 6
	s_add_i32 s98, s98, 0x4a00
	v_mov_b32_e32 v250, s98
	v_mov_b32_e32 v251, 1
	global_atomic_add v252, v250, v251, s[66:67] sc0
	buffer_inv sc1
	s_lshr_b32 s98, s64, 3
	s_mul_i32 s98, s98, 1
	s_add_i32 s98, s98, -1
	v_add_u32_e32 v250, 0x200, v250
	s_waitcnt vmcnt(0)
	v_readfirstlane_b32 s99, v252
	s_cmp_eq_u32 s99, s98
	s_cbranch_scc0 .Lgb_wait_0
	global_atomic_add v250, v251, s[66:67]
	s_waitcnt vmcnt(0)
	s_branch .Lgb_done_0
.Lgb_wait_0:
	s_mov_b32 s99, 0
.Lgb_spin_0:
	global_load_dword v252, v250, s[66:67] sc1
	s_waitcnt vmcnt(0)
	v_readfirstlane_b32 s98, v252
	s_cmp_gt_u32 s98, 0
	s_cbranch_scc1 .Lgb_done_0
	s_sleep 1
	s_add_i32 s99, s99, 1
	s_cmp_lt_u32 s99, 0x8000
	s_cbranch_scc1 .Lgb_spin_0
.Lgb_done_0:
	s_or_b64 exec, exec, s[0:1]
	s_branch .Lgb_skip_0

.Lgb_skip_0:
	s_mov_b64 s[0:1], s[66:67]
	s_waitcnt lgkmcnt(0)
	v_mov_b32_e32 v0, 0
	s_mov_b64 s[12:13], s[68:69]
	v_mov_b32_e32 v1, v194
	s_mov_b32 s38, s64
	s_barrier
	global_load_dwordx2 v[128:129], v0, s[0:1]
	v_mov_b32_e32 v8, v194
	v_cndmask_b32_e64 v0, 0, 1, s[10:11]
	v_cmp_ne_u32_e64 s[4:5], 1, v0
	s_andn2_b64 vcc, exec, s[10:11]
	v_readfirstlane_b32 s8, v8
	s_cbranch_vccnz .LBB0_515
	s_lshr_b32 s6, s3, 29
	s_add_i32 s9, s2, s6
	s_and_b32 s6, s9, -8
	s_sub_i32 s10, s2, s6
	s_cmp_gt_i32 s10, -1
	s_cbranch_scc0 .LBB0_512
	s_lshl_b32 s11, s10, 5
	s_cbranch_execz .LBB0_513
	s_branch .LBB0_514

.LBB0_1554:
	s_cmp_eq_u32 s100, 1
	s_cbranch_scc0 .Lgb_full_1
	s_waitcnt vmcnt(0)
	s_barrier
	s_and_saveexec_b64 s[0:1], s[46:47]
	s_cbranch_execz .Lgb_done_1
	s_and_b32 s98, s2, 7
	s_lshl_b32 s98, s98, 6
	s_add_i32 s98, s98, 0x4a00
	v_mov_b32_e32 v250, s98
	v_mov_b32_e32 v251, 1
	global_atomic_add v252, v250, v251, s[66:67] sc0
	buffer_inv sc1
	s_lshr_b32 s98, s64, 3
	s_mul_i32 s98, s98, 2
	s_add_i32 s98, s98, -1
	v_add_u32_e32 v250, 0x200, v250
	s_waitcnt vmcnt(0)
	v_readfirstlane_b32 s99, v252
	s_cmp_eq_u32 s99, s98
	s_cbranch_scc0 .Lgb_wait_1
	global_atomic_add v250, v251, s[66:67]
	s_waitcnt vmcnt(0)
	s_branch .Lgb_done_1

.Lgb_spin_1:
	global_load_dword v252, v250, s[66:67] sc1
	s_waitcnt vmcnt(0)
	v_readfirstlane_b32 s98, v252
	s_cmp_gt_u32 s98, 1
	s_cbranch_scc1 .Lgb_done_1
	s_sleep 1
	s_add_i32 s99, s99, 1
	s_cmp_lt_u32 s99, 0x8000
	s_cbranch_scc1 .Lgb_spin_1

.Lgb_skip_1:
	s_mov_b64 s[6:7], s[66:67]
	s_mov_b64 s[0:1], s[68:69]
	s_waitcnt lgkmcnt(0)
	v_mov_b32_e32 v0, v194
	s_mov_b32 s51, s64
	v_mov_b32_e32 v8, v194
	s_barrier
	s_and_b64 vcc, exec, s[4:5]
	v_readfirstlane_b32 s26, v8
	s_cbranch_vccnz .LBB0_1612
	s_lshr_b32 s14, s3, 29
	s_add_i32 s16, s2, s14
	s_and_b32 s14, s16, -8
	s_sub_i32 s17, s2, s14
	s_cmp_gt_i32 s17, -1
	s_cbranch_scc0 .LBB0_1609
	s_lshl_b32 s18, s17, 5
	s_cbranch_execz .LBB0_1610
	s_branch .LBB0_1611

.LBB0_1716:
	s_cmp_eq_u32 s100, 1
	s_cbranch_scc0 .Lgb_full_2
	s_waitcnt vmcnt(0)
	s_barrier
	s_and_saveexec_b64 s[0:1], s[46:47]
	s_cbranch_execz .Lgb_done_2
	s_and_b32 s98, s2, 7
	s_lshl_b32 s98, s98, 6
	s_add_i32 s98, s98, 0x4a00
	v_mov_b32_e32 v250, s98
	v_mov_b32_e32 v251, 1
	global_atomic_add v252, v250, v251, s[66:67] sc0
	buffer_inv sc1
	s_lshr_b32 s98, s64, 3
	s_mul_i32 s98, s98, 3
	s_add_i32 s98, s98, -1
	v_add_u32_e32 v250, 0x200, v250
	s_waitcnt vmcnt(0)
	v_readfirstlane_b32 s99, v252
	s_cmp_eq_u32 s99, s98
	s_cbranch_scc0 .Lgb_wait_2
	global_atomic_add v250, v251, s[66:67]
	s_waitcnt vmcnt(0)
	s_branch .Lgb_done_2

.Lgb_spin_2:
	global_load_dword v252, v250, s[66:67] sc1
	s_waitcnt vmcnt(0)
	v_readfirstlane_b32 s98, v252
	s_cmp_gt_u32 s98, 2
	s_cbranch_scc1 .Lgb_done_2
	s_sleep 1
	s_add_i32 s99, s99, 1
	s_cmp_lt_u32 s99, 0x8000
	s_cbranch_scc1 .Lgb_spin_2

.Lgb_skip_2:
	s_mov_b64 s[0:1], s[66:67]
	s_mov_b64 s[18:19], s[68:69]
	s_waitcnt lgkmcnt(0)
	v_mov_b32_e32 v0, v194
	s_mov_b32 s44, s64
	v_mov_b32_e32 v8, v194
	s_barrier
	s_and_b64 vcc, exec, s[4:5]
	v_readfirstlane_b32 s16, v8
	s_cbranch_vccnz .LBB0_1774
	s_lshr_b32 s14, s3, 29
	s_add_i32 s17, s2, s14
	s_and_b32 s14, s17, -8
	s_sub_i32 s20, s2, s14
	s_cmp_gt_i32 s20, -1
	s_cbranch_scc0 .LBB0_1771
	s_lshl_b32 s21, s20, 5
	s_cbranch_execz .LBB0_1772
	s_branch .LBB0_1773

.LBB0_2067:
	s_cmp_eq_u32 s100, 1
	s_cbranch_scc0 .Lgb_full_3
	s_waitcnt vmcnt(0)
	s_barrier
	s_and_saveexec_b64 s[0:1], s[46:47]
	s_cbranch_execz .Lgb_done_3
	s_and_b32 s98, s2, 7
	s_lshl_b32 s98, s98, 6
	s_add_i32 s98, s98, 0x4a00
	v_mov_b32_e32 v250, s98
	v_mov_b32_e32 v251, 1
	global_atomic_add v252, v250, v251, s[66:67] sc0
	buffer_inv sc1
	s_lshr_b32 s98, s64, 3
	s_mul_i32 s98, s98, 4
	s_add_i32 s98, s98, -1
	v_add_u32_e32 v250, 0x200, v250
	s_waitcnt vmcnt(0)
	v_readfirstlane_b32 s99, v252
	s_cmp_eq_u32 s99, s98
	s_cbranch_scc0 .Lgb_wait_3
	global_atomic_add v250, v251, s[66:67]
	s_waitcnt vmcnt(0)
	s_branch .Lgb_done_3

.Lgb_spin_3:
	global_load_dword v252, v250, s[66:67] sc1
	s_waitcnt vmcnt(0)
	v_readfirstlane_b32 s98, v252
	s_cmp_gt_u32 s98, 3
	s_cbranch_scc1 .Lgb_done_3
	s_sleep 1
	s_add_i32 s99, s99, 1
	s_cmp_lt_u32 s99, 0x8000
	s_cbranch_scc1 .Lgb_spin_3

.LBB0_3164:
	s_cmp_eq_u32 s100, 1
	s_cbranch_scc0 .Lgb_full_4
	s_waitcnt vmcnt(0)
	s_barrier
	s_and_saveexec_b64 s[0:1], s[46:47]
	s_cbranch_execz .Lgb_done_4
	s_and_b32 s98, s2, 7
	s_lshl_b32 s98, s98, 6
	s_add_i32 s98, s98, 0x4a00
	v_mov_b32_e32 v250, s98
	v_mov_b32_e32 v251, 1
	global_atomic_add v252, v250, v251, s[66:67] sc0
	buffer_inv sc1
	s_lshr_b32 s98, s64, 3
	s_mul_i32 s98, s98, 5
	s_add_i32 s98, s98, -1
	v_add_u32_e32 v250, 0x200, v250
	s_waitcnt vmcnt(0)
	v_readfirstlane_b32 s99, v252
	s_cmp_eq_u32 s99, s98
	s_cbranch_scc0 .Lgb_wait_4
	global_atomic_add v250, v251, s[66:67]
	s_waitcnt vmcnt(0)
	s_branch .Lgb_done_4

.Lgb_spin_4:
	global_load_dword v252, v250, s[66:67] sc1
	s_waitcnt vmcnt(0)
	v_readfirstlane_b32 s98, v252
	s_cmp_gt_u32 s98, 4
	s_cbranch_scc1 .Lgb_done_4
	s_sleep 1
	s_add_i32 s99, s99, 1
	s_cmp_lt_u32 s99, 0x8000
	s_cbranch_scc1 .Lgb_spin_4

.Lgb_skip_4:
	s_mov_b64 s[8:9], s[66:67]
	s_mov_b64 s[0:1], s[68:69]
	s_waitcnt vmcnt(0) lgkmcnt(0)
	v_mov_b32_e32 v0, v194
	s_mov_b32 s42, s64
	v_mov_b32_e32 v8, v194
	s_barrier
	s_and_b64 vcc, exec, s[4:5]
	v_readfirstlane_b32 s22, v8
	s_cbranch_vccnz .LBB0_3222
	s_lshr_b32 s10, s3, 29
	s_add_i32 s12, s2, s10
	s_and_b32 s10, s12, -8
	s_sub_i32 s13, s2, s10
	s_cmp_gt_i32 s13, -1
	s_cbranch_scc0 .LBB0_3219
	s_lshl_b32 s14, s13, 5
	s_cbranch_execz .LBB0_3220
	s_branch .LBB0_3221

.LBB0_3326:
	s_cmp_eq_u32 s100, 1
	s_cbranch_scc0 .Lgb_full_5
	s_waitcnt vmcnt(0)
	s_barrier
	s_and_saveexec_b64 s[0:1], s[46:47]
	s_cbranch_execz .Lgb_done_5
	s_and_b32 s98, s2, 7
	s_lshl_b32 s98, s98, 6
	s_add_i32 s98, s98, 0x4a00
	v_mov_b32_e32 v250, s98
	v_mov_b32_e32 v251, 1
	global_atomic_add v252, v250, v251, s[66:67] sc0
	buffer_inv sc1
	s_lshr_b32 s98, s64, 3
	s_mul_i32 s98, s98, 6
	s_add_i32 s98, s98, -1
	v_add_u32_e32 v250, 0x200, v250
	s_waitcnt vmcnt(0)
	v_readfirstlane_b32 s99, v252
	s_cmp_eq_u32 s99, s98
	s_cbranch_scc0 .Lgb_wait_5
	global_atomic_add v250, v251, s[66:67]
	s_waitcnt vmcnt(0)
	s_branch .Lgb_done_5

.Lgb_spin_5:
	global_load_dword v252, v250, s[66:67] sc1
	s_waitcnt vmcnt(0)
	v_readfirstlane_b32 s98, v252
	s_cmp_gt_u32 s98, 5
	s_cbranch_scc1 .Lgb_done_5
	s_sleep 1
	s_add_i32 s99, s99, 1
	s_cmp_lt_u32 s99, 0x8000
	s_cbranch_scc1 .Lgb_spin_5

.Lgb_skip_5:
	s_mov_b64 s[0:1], s[66:67]
	s_mov_b64 s[8:9], s[68:69]
	s_waitcnt lgkmcnt(0)
	v_mov_b32_e32 v0, v194
	s_mov_b32 s30, s64
	v_mov_b32_e32 v8, v194
	s_barrier
	s_and_b64 vcc, exec, s[4:5]
	v_readfirstlane_b32 s18, v8
	s_cbranch_vccnz .LBB0_3384
	s_lshr_b32 s6, s3, 29
	s_add_i32 s12, s2, s6
	s_and_b32 s6, s12, -8
	s_sub_i32 s10, s2, s6
	s_cmp_gt_i32 s10, -1
	s_cbranch_scc0 .LBB0_3381
	s_lshl_b32 s11, s10, 5
	s_ashr_i32 s6, s12, 3
	s_cbranch_execz .LBB0_3382
	s_branch .LBB0_3383

	.amdhsa_kernel _Z10fwd_kernel4Args
		.amdhsa_group_segment_fixed_size 0
		.amdhsa_private_segment_fixed_size 0
		.amdhsa_kernarg_size 528
		.amdhsa_user_sgpr_count 2
		.amdhsa_user_sgpr_dispatch_ptr 0
		.amdhsa_user_sgpr_queue_ptr 0
		.amdhsa_user_sgpr_kernarg_segment_ptr 1
		.amdhsa_user_sgpr_dispatch_id 0
		.amdhsa_user_sgpr_kernarg_preload_length 0
		.amdhsa_user_sgpr_kernarg_preload_offset 0
		.amdhsa_user_sgpr_private_segment_size 0
		.amdhsa_uses_dynamic_stack 0
		.amdhsa_enable_private_segment 0
		.amdhsa_system_sgpr_workgroup_id_x 1
		.amdhsa_system_sgpr_workgroup_id_y 0
		.amdhsa_system_sgpr_workgroup_id_z 0
		.amdhsa_system_sgpr_workgroup_info 0
		.amdhsa_system_vgpr_workitem_id 2
		.amdhsa_next_free_vgpr 256
		.amdhsa_next_free_sgpr 102
		.amdhsa_accum_offset 256
		.amdhsa_reserve_vcc 1
		.amdhsa_float_round_mode_32 0
		.amdhsa_float_round_mode_16_64 0
		.amdhsa_float_denorm_mode_32 3
		.amdhsa_float_denorm_mode_16_64 3
		.amdhsa_dx10_clamp 1
		.amdhsa_ieee_mode 1
		.amdhsa_fp16_overflow 0
		.amdhsa_tg_split 0
		.amdhsa_exception_fp_ieee_invalid_op 0
		.amdhsa_exception_fp_denorm_src 0
		.amdhsa_exception_fp_ieee_div_zero 0
		.amdhsa_exception_fp_ieee_overflow 0
		.amdhsa_exception_fp_ieee_underflow 0
		.amdhsa_exception_fp_ieee_inexact 0
		.amdhsa_exception_int_div_zero 0
	.end_amdhsa_kernel

.Lfunc_end0:
	.size	_Z10fwd_kernel4Args, .Lfunc_end0-_Z10fwd_kernel4Args
	.set _Z10fwd_kernel4Args.num_vgpr, 256
	.set _Z10fwd_kernel4Args.num_agpr, 0
	.set _Z10fwd_kernel4Args.numbered_sgpr, 102
	.set _Z10fwd_kernel4Args.num_named_barrier, 0
	.set _Z10fwd_kernel4Args.private_seg_size, 0
	.set _Z10fwd_kernel4Args.uses_vcc, 1
	.set _Z10fwd_kernel4Args.uses_flat_scratch, 0
	.set _Z10fwd_kernel4Args.has_dyn_sized_stack, 0
	.set _Z10fwd_kernel4Args.has_recursion, 0
	.set _Z10fwd_kernel4Args.has_indirect_call, 0

amdhsa.kernels:
  - .agpr_count:     0
    .args:
      - .offset:         0
        .size:           272
        .value_kind:     by_value
      - .offset:         272
        .size:           4
        .value_kind:     hidden_block_count_x
      - .offset:         276
        .size:           4
        .value_kind:     hidden_block_count_y
      - .offset:         280
        .size:           4
        .value_kind:     hidden_block_count_z
      - .offset:         284
        .size:           2
        .value_kind:     hidden_group_size_x
      - .offset:         286
        .size:           2
        .value_kind:     hidden_group_size_y
      - .offset:         288
        .size:           2
        .value_kind:     hidden_group_size_z
      - .offset:         290
        .size:           2
        .value_kind:     hidden_remainder_x
      - .offset:         292
        .size:           2
        .value_kind:     hidden_remainder_y
      - .offset:         294
        .size:           2
        .value_kind:     hidden_remainder_z
      - .offset:         312
        .size:           8
        .value_kind:     hidden_global_offset_x
      - .offset:         320
        .size:           8
        .value_kind:     hidden_global_offset_y
      - .offset:         328
        .size:           8
        .value_kind:     hidden_global_offset_z
      - .offset:         336
        .size:           2
        .value_kind:     hidden_grid_dims
      - .offset:         360
        .size:           8
        .value_kind:     hidden_multigrid_sync_arg
      - .offset:         392
        .size:           4
        .value_kind:     hidden_dynamic_lds_size
    .group_segment_fixed_size: 0
    .kernarg_segment_align: 8
    .kernarg_segment_size: 528
    .language:       OpenCL C
    .language_version:
      - 2
      - 0
    .max_flat_workgroup_size: 512
    .name:           _Z10fwd_kernel4Args
    .private_segment_fixed_size: 0
    .sgpr_count:     108
    .sgpr_spill_count: 0
    .symbol:         _Z10fwd_kernel4Args.kd
    .uniform_work_group_size: 1
    .uses_dynamic_stack: false
    .vgpr_count:     256
    .vgpr_spill_count: 0
    .wavefront_size: 64
